# attention leader+follower loops: K/V fragment ds_reads rotated over 4 buffers with counted lgkmcnt (arithmetic unchanged); testing theory that loops were LDS-latency bound
# baseline (speedup 1.0000x reference)
.LBB0_226:
	v_cvt_f32_i32_e32 v162, v127
	s_lshl_b32 s86, s33, 15
	v_or_b32_e32 v102, s86, v200
	s_waitcnt lgkmcnt(0)
	v_add_f32_e32 v80, 1.0, v162
	v_pk_add_f32 v[66:67], v[162:163], s[12:13] op_sel_hi:[0,1]
	v_pk_add_f32 v[68:69], v[162:163], s[16:17] op_sel_hi:[0,1]
	v_pk_add_f32 v[70:71], v[162:163], s[18:19] op_sel_hi:[0,1]
	v_pk_add_f32 v[72:73], v[162:163], s[20:21] op_sel_hi:[0,1]
	v_pk_add_f32 v[74:75], v[162:163], s[22:23] op_sel_hi:[0,1]
	v_pk_add_f32 v[76:77], v[162:163], s[26:27] op_sel_hi:[0,1]
	v_pk_add_f32 v[78:79], v[162:163], s[28:29] op_sel_hi:[0,1]
	s_barrier
	v_and_b32_e32 v67, 0x7fffffff, v67
	v_and_b32_e32 v66, 0x7fffffff, v66
	v_and_b32_e32 v69, 0x7fffffff, v69
	v_and_b32_e32 v68, 0x7fffffff, v68
	v_and_b32_e32 v71, 0x7fffffff, v71
	v_and_b32_e32 v70, 0x7fffffff, v70
	v_and_b32_e32 v73, 0x7fffffff, v73
	v_and_b32_e32 v72, 0x7fffffff, v72
	v_and_b32_e32 v75, 0x7fffffff, v75
	v_and_b32_e32 v74, 0x7fffffff, v74
	v_and_b32_e32 v77, 0x7fffffff, v77
	v_and_b32_e32 v76, 0x7fffffff, v76
	v_and_b32_e32 v79, 0x7fffffff, v79
	v_and_b32_e32 v78, 0x7fffffff, v78
	v_and_b32_e32 v98, 0x7fffffff, v162
	v_and_b32_e32 v99, 0x7fffffff, v80
	v_mov_b32_e32 v147, v146
	v_add_u32_e32 v129, v102, v202
	v_add_u32_e32 v151, v102, v203
	v_add_u32_e32 v157, v102, v204
	v_add_u32_e32 v161, v102, v205
	ds_read_b128 v[108:111], v129
	ds_read_b128 v[112:115], v151
	ds_read_b128 v[116:119], v157
	ds_read_b128 v[250:253], v161
	v_pk_fma_f32 v[80:81], v[106:107], v[78:79], v[146:147]
	v_pk_fma_f32 v[78:79], v[106:107], v[76:77], v[146:147]
	v_pk_fma_f32 v[76:77], v[106:107], v[74:75], v[146:147]
	v_pk_fma_f32 v[74:75], v[106:107], v[72:73], v[146:147]
	v_pk_fma_f32 v[72:73], v[106:107], v[70:71], v[146:147]
	v_pk_fma_f32 v[70:71], v[106:107], v[68:69], v[146:147]
	v_pk_fma_f32 v[68:69], v[106:107], v[66:67], v[146:147]
	v_pk_fma_f32 v[66:67], v[106:107], v[98:99], v[148:149]
	s_waitcnt vmcnt(3) lgkmcnt(3)
	s_nop 0
	v_mfma_f32_32x32x16_bf16 v[66:81], v[108:111], v[82:85], v[66:81]
	ds_read_b128 v[108:111], v129 offset:8192
	s_add_i32 s6, s33, 1
	v_add_u32_e32 v128, 1, v128
	s_cmp_lg_u32 s33, 2
	v_cmp_ge_i32_e32 vcc, v128, v155
	s_waitcnt vmcnt(2) lgkmcnt(3)
	v_mfma_f32_32x32x16_bf16 v[66:81], v[112:115], v[86:89], v[66:81]
	ds_read_b128 v[112:115], v151 offset:8192
	s_cselect_b32 s33, s6, 0
	v_add_u32_e32 v127, 64, v127
	s_or_b64 s[84:85], vcc, s[84:85]
	s_waitcnt vmcnt(1) lgkmcnt(3)
	v_mfma_f32_32x32x16_bf16 v[66:81], v[116:119], v[90:93], v[66:81]
	ds_read_b128 v[116:119], v157 offset:8192
	s_waitcnt vmcnt(0) lgkmcnt(3)
	v_mfma_f32_32x32x16_bf16 v[66:81], v[250:253], v[94:97], v[66:81]
	ds_read_b128 v[250:253], v161 offset:8192
	s_nop 11
	v_exp_f32_e32 v66, v66
	v_exp_f32_e32 v166, v67
	v_exp_f32_e32 v168, v68
	v_exp_f32_e32 v170, v69
	v_add_f32_e32 v132, 0, v66
	v_exp_f32_e32 v188, v78
	v_exp_f32_e32 v212, v79
	v_exp_f32_e32 v214, v80
	v_exp_f32_e32 v216, v81
	v_cvt_pk_bf16_f32 v98, v66, v166
	v_pk_add_f32 v[66:67], v[162:163], s[30:31] op_sel_hi:[0,1]
	v_pk_add_f32 v[68:69], v[162:163], s[34:35] op_sel_hi:[0,1]
	v_pk_add_f32 v[78:79], v[162:163], s[64:65] op_sel_hi:[0,1]
	v_pk_add_f32 v[80:81], v[162:163], s[74:75] op_sel_hi:[0,1]
	v_exp_f32_e32 v172, v70
	v_exp_f32_e32 v174, v71
	v_exp_f32_e32 v176, v72
	v_exp_f32_e32 v178, v73
	v_exp_f32_e32 v180, v74
	v_exp_f32_e32 v182, v75
	v_exp_f32_e32 v184, v76
	v_exp_f32_e32 v186, v77
	v_pk_add_f32 v[70:71], v[162:163], s[48:49] op_sel_hi:[0,1]
	v_pk_add_f32 v[72:73], v[162:163], s[54:55] op_sel_hi:[0,1]
	v_pk_add_f32 v[74:75], v[162:163], s[56:57] op_sel_hi:[0,1]
	v_pk_add_f32 v[76:77], v[162:163], s[58:59] op_sel_hi:[0,1]
	v_and_b32_e32 v163, 0x7fffffff, v81
	v_and_b32_e32 v162, 0x7fffffff, v80
	v_and_b32_e32 v165, 0x7fffffff, v79
	v_and_b32_e32 v164, 0x7fffffff, v78
	v_and_b32_e32 v69, 0x7fffffff, v69
	v_and_b32_e32 v68, 0x7fffffff, v68
	v_and_b32_e32 v67, 0x7fffffff, v67
	v_and_b32_e32 v66, 0x7fffffff, v66
	v_pk_fma_f32 v[80:81], v[106:107], v[66:67], v[146:147]
	v_pk_fma_f32 v[78:79], v[106:107], v[68:69], v[146:147]
	v_pk_fma_f32 v[68:69], v[106:107], v[164:165], v[146:147]
	v_pk_fma_f32 v[66:67], v[106:107], v[162:163], v[148:149]
	v_and_b32_e32 v219, 0x7fffffff, v77
	v_and_b32_e32 v218, 0x7fffffff, v76
	v_and_b32_e32 v221, 0x7fffffff, v75
	v_and_b32_e32 v220, 0x7fffffff, v74
	v_and_b32_e32 v73, 0x7fffffff, v73
	v_and_b32_e32 v72, 0x7fffffff, v72
	v_and_b32_e32 v71, 0x7fffffff, v71
	v_and_b32_e32 v70, 0x7fffffff, v70
	v_pk_fma_f32 v[76:77], v[106:107], v[70:71], v[146:147]
	v_pk_fma_f32 v[74:75], v[106:107], v[72:73], v[146:147]
	v_pk_fma_f32 v[72:73], v[106:107], v[220:221], v[146:147]
	v_pk_fma_f32 v[70:71], v[106:107], v[218:219], v[146:147]
	v_cvt_pk_bf16_f32 v99, v168, v170
	v_cvt_pk_bf16_f32 v100, v172, v174
	s_waitcnt lgkmcnt(3)
	v_mfma_f32_32x32x16_bf16 v[66:81], v[108:111], v[82:85], v[66:81]
	v_cvt_pk_bf16_f32 v101, v176, v178
	v_cvt_pk_bf16_f32 v102, v180, v182
	v_cvt_pk_bf16_f32 v103, v184, v186
	v_cvt_pk_bf16_f32 v104, v188, v212
	v_cvt_pk_bf16_f32 v105, v214, v216
	s_waitcnt lgkmcnt(2)
	v_mfma_f32_32x32x16_bf16 v[66:81], v[112:115], v[86:89], v[66:81]
	s_waitcnt lgkmcnt(1)
	v_mfma_f32_32x32x16_bf16 v[66:81], v[116:119], v[90:93], v[66:81]
	s_waitcnt lgkmcnt(0)
	s_barrier
	s_waitcnt lgkmcnt(0)
	v_mfma_f32_32x32x16_bf16 v[66:81], v[250:253], v[94:97], v[66:81]
	s_nop 11
	v_exp_f32_e32 v217, v80
	v_or_b32_e32 v80, s86, v193
	v_exp_f32_e32 v161, v81
	v_add_u32_e32 v81, v80, v195
	v_exp_f32_e32 v183, v74
	v_exp_f32_e32 v185, v75
	v_exp_f32_e32 v187, v76
	v_exp_f32_e32 v189, v77
	v_add_u32_e32 v129, v80, v196
	ds_read_b128 v[108:111], v81 offset:16384
	ds_read_b128 v[112:115], v129 offset:16384
	ds_read_b128 v[116:119], v81 offset:20480
	ds_read_b128 v[250:253], v129 offset:20480
	s_waitcnt lgkmcnt(3)
	v_mfma_f32_32x32x16_bf16 v[50:65], v[108:111], v[98:101], v[50:65]
	ds_read_b128 v[108:111], v81 offset:24576
	v_exp_f32_e32 v167, v66
	v_exp_f32_e32 v169, v67
	v_exp_f32_e32 v171, v68
	v_exp_f32_e32 v173, v69
	v_pk_add_f32 v[66:67], v[166:167], v[132:133]
	v_exp_f32_e32 v175, v70
	s_waitcnt lgkmcnt(3)
	v_mfma_f32_32x32x16_bf16 v[50:65], v[112:115], v[102:105], v[50:65]
	ds_read_b128 v[112:115], v129 offset:24576
	v_add_f32_e64 v66, v168, v66
	v_add_f32_e64 v67, v169, v67
	v_exp_f32_e32 v177, v71
	v_pk_add_f32 v[66:67], v[170:171], v[66:67]
	v_exp_f32_e32 v179, v72
	v_pk_add_f32 v[66:67], v[172:173], v[66:67]
	v_exp_f32_e32 v181, v73
	s_waitcnt lgkmcnt(3)
	v_mfma_f32_32x32x16_bf16 v[34:49], v[116:119], v[98:101], v[34:49]
	ds_read_b128 v[116:119], v81 offset:28672
	v_add_f32_e64 v66, v174, v66
	v_add_f32_e64 v67, v175, v67
	v_exp_f32_e32 v213, v78
	v_pk_add_f32 v[66:67], v[176:177], v[66:67]
	v_exp_f32_e32 v215, v79
	v_pk_add_f32 v[66:67], v[178:179], v[66:67]
	v_cvt_pk_bf16_f32 v68, v175, v177
	s_waitcnt lgkmcnt(3)
	v_mfma_f32_32x32x16_bf16 v[34:49], v[250:253], v[102:105], v[34:49]
	v_add_u32_e32 v81, v80, v197
	v_add_u32_e32 v80, v80, v198
	ds_read_b128 v[250:253], v129 offset:28672
	v_add_f32_e64 v66, v180, v66
	v_add_f32_e64 v67, v181, v67
	v_cvt_pk_bf16_f32 v69, v179, v181
	v_add_f32_e64 v66, v182, v66
	v_add_f32_e64 v67, v183, v67
	v_cvt_pk_bf16_f32 v70, v183, v185
	v_pk_add_f32 v[66:67], v[184:185], v[66:67]
	v_cvt_pk_bf16_f32 v71, v187, v189
	s_waitcnt lgkmcnt(3)
	v_mfma_f32_32x32x16_bf16 v[18:33], v[108:111], v[98:101], v[18:33]
	ds_read_b128 v[108:111], v81 offset:16384
	v_add_f32_e64 v66, v186, v66
	v_add_f32_e64 v67, v187, v67
	v_cvt_pk_bf16_f32 v72, v213, v215
	v_add_f32_e64 v66, v188, v66
	v_add_f32_e64 v67, v189, v67
	v_cvt_pk_bf16_f32 v73, v217, v161
	v_pk_add_f32 v[66:67], v[212:213], v[66:67]
	s_waitcnt lgkmcnt(3)
	v_mfma_f32_32x32x16_bf16 v[18:33], v[112:115], v[102:105], v[18:33]
	ds_read_b128 v[112:115], v80 offset:16384
	v_add_f32_e64 v66, v214, v66
	v_add_f32_e64 v67, v215, v67
	v_pk_add_f32 v[66:67], v[216:217], v[66:67]
	s_nop 0
	v_pk_add_f32 v[78:79], v[160:161], v[66:67]
	s_waitcnt lgkmcnt(3)
	v_mfma_f32_32x32x16_bf16 v[2:17], v[116:119], v[98:101], v[2:17]
	ds_read_b128 v[116:119], v81 offset:20480
	v_cvt_pk_bf16_f32 v66, v167, v169
	v_cvt_pk_bf16_f32 v67, v171, v173
	v_add_f32_e32 v160, v78, v79
	s_waitcnt lgkmcnt(3)
	v_mfma_f32_32x32x16_bf16 v[2:17], v[250:253], v[102:105], v[2:17]
	ds_read_b128 v[250:253], v80 offset:20480
	s_waitcnt lgkmcnt(3)
	v_mfma_f32_32x32x16_bf16 v[50:65], v[108:111], v[66:69], v[50:65]
	ds_read_b128 v[108:111], v81 offset:24576
	s_waitcnt lgkmcnt(3)
	v_mfma_f32_32x32x16_bf16 v[50:65], v[112:115], v[70:73], v[50:65]
	ds_read_b128 v[112:115], v80 offset:24576
	s_waitcnt lgkmcnt(3)
	v_mfma_f32_32x32x16_bf16 v[34:49], v[116:119], v[66:69], v[34:49]
	ds_read_b128 v[116:119], v81 offset:28672
	s_waitcnt lgkmcnt(3)
	v_mfma_f32_32x32x16_bf16 v[34:49], v[250:253], v[70:73], v[34:49]
	ds_read_b128 v[250:253], v80 offset:28672
	s_waitcnt lgkmcnt(3)
	v_mfma_f32_32x32x16_bf16 v[18:33], v[108:111], v[66:69], v[18:33]
	s_waitcnt lgkmcnt(2)
	v_mfma_f32_32x32x16_bf16 v[18:33], v[112:115], v[70:73], v[18:33]
	s_waitcnt lgkmcnt(1)
	v_mfma_f32_32x32x16_bf16 v[2:17], v[116:119], v[66:69], v[2:17]
	s_waitcnt lgkmcnt(0)
	v_mfma_f32_32x32x16_bf16 v[2:17], v[250:253], v[70:73], v[2:17]
	s_andn2_b64 exec, exec, s[84:85]
	s_cbranch_execnz .LBB0_226
	s_or_b64 exec, exec, s[84:85]

.LBB0_232:
	s_or_b64 exec, exec, s[86:87]
	v_add_u32_e32 v66, v151, v66
	v_cvt_f32_i32_e32 v212, v66
	s_and_b64 s[6:7], exec, vcc
	s_or_b64 s[84:85], s[6:7], s[84:85]
	s_lshl_b32 s86, s90, 15
	v_or_b32_e32 v102, s86, v200
	v_add_f32_e32 v80, 1.0, v212
	v_pk_add_f32 v[66:67], v[212:213], s[12:13] op_sel_hi:[0,1]
	v_pk_add_f32 v[68:69], v[212:213], s[16:17] op_sel_hi:[0,1]
	v_pk_add_f32 v[70:71], v[212:213], s[18:19] op_sel_hi:[0,1]
	v_pk_add_f32 v[72:73], v[212:213], s[20:21] op_sel_hi:[0,1]
	v_pk_add_f32 v[74:75], v[212:213], s[22:23] op_sel_hi:[0,1]
	v_pk_add_f32 v[76:77], v[212:213], s[26:27] op_sel_hi:[0,1]
	v_pk_add_f32 v[78:79], v[212:213], s[28:29] op_sel_hi:[0,1]
	v_and_b32_e32 v67, 0x7fffffff, v67
	v_and_b32_e32 v66, 0x7fffffff, v66
	v_and_b32_e32 v69, 0x7fffffff, v69
	v_and_b32_e32 v68, 0x7fffffff, v68
	v_and_b32_e32 v71, 0x7fffffff, v71
	v_and_b32_e32 v70, 0x7fffffff, v70
	v_and_b32_e32 v73, 0x7fffffff, v73
	v_and_b32_e32 v72, 0x7fffffff, v72
	v_and_b32_e32 v75, 0x7fffffff, v75
	v_and_b32_e32 v74, 0x7fffffff, v74
	v_and_b32_e32 v77, 0x7fffffff, v77
	v_and_b32_e32 v76, 0x7fffffff, v76
	v_and_b32_e32 v79, 0x7fffffff, v79
	v_and_b32_e32 v78, 0x7fffffff, v78
	v_and_b32_e32 v98, 0x7fffffff, v212
	v_and_b32_e32 v99, 0x7fffffff, v80
	v_mov_b32_e32 v147, v146
	v_add_u32_e32 v127, v102, v202
	v_add_u32_e32 v129, v102, v203
	v_add_u32_e32 v157, v102, v204
	v_add_u32_e32 v161, v102, v205
	ds_read_b128 v[112:115], v127
	ds_read_b128 v[116:119], v129
	ds_read_b128 v[120:123], v157
	ds_read_b128 v[250:253], v161
	v_pk_fma_f32 v[80:81], v[110:111], v[78:79], v[146:147]
	v_pk_fma_f32 v[78:79], v[110:111], v[76:77], v[146:147]
	v_pk_fma_f32 v[76:77], v[110:111], v[74:75], v[146:147]
	v_pk_fma_f32 v[74:75], v[110:111], v[72:73], v[146:147]
	v_pk_fma_f32 v[72:73], v[110:111], v[70:71], v[146:147]
	v_pk_fma_f32 v[70:71], v[110:111], v[68:69], v[146:147]
	v_pk_fma_f32 v[68:69], v[110:111], v[66:67], v[146:147]
	v_pk_fma_f32 v[66:67], v[110:111], v[98:99], v[148:149]
	s_waitcnt lgkmcnt(3)
	s_nop 0
	v_mfma_f32_32x32x16_bf16 v[66:81], v[112:115], v[82:85], v[66:81]
	ds_read_b128 v[112:115], v127 offset:8192
	v_add_u32_e32 v141, 1, v141
	s_mov_b32 s90, s33
	s_waitcnt lgkmcnt(3)
	v_mfma_f32_32x32x16_bf16 v[66:81], v[116:119], v[86:89], v[66:81]
	ds_read_b128 v[116:119], v129 offset:8192
	s_waitcnt lgkmcnt(3)
	v_mfma_f32_32x32x16_bf16 v[66:81], v[120:123], v[90:93], v[66:81]
	ds_read_b128 v[120:123], v157 offset:8192
	s_waitcnt lgkmcnt(3)
	v_mfma_f32_32x32x16_bf16 v[66:81], v[250:253], v[94:97], v[66:81]
	ds_read_b128 v[250:253], v161 offset:8192
	s_nop 11
	v_exp_f32_e32 v66, v66
	v_exp_f32_e32 v128, v67
	v_exp_f32_e32 v164, v68
	v_exp_f32_e32 v162, v69
	v_add_f32_e32 v132, 0, v66
	v_exp_f32_e32 v184, v78
	v_exp_f32_e32 v182, v79
	v_exp_f32_e32 v188, v80
	v_exp_f32_e32 v186, v81
	v_cvt_pk_bf16_f32 v102, v66, v128
	v_pk_add_f32 v[66:67], v[212:213], s[30:31] op_sel_hi:[0,1]
	v_pk_add_f32 v[68:69], v[212:213], s[34:35] op_sel_hi:[0,1]
	v_pk_add_f32 v[78:79], v[212:213], s[64:65] op_sel_hi:[0,1]
	v_pk_add_f32 v[80:81], v[212:213], s[74:75] op_sel_hi:[0,1]
	v_exp_f32_e32 v168, v70
	v_exp_f32_e32 v166, v71
	v_exp_f32_e32 v172, v72
	v_exp_f32_e32 v170, v73
	v_exp_f32_e32 v176, v74
	v_exp_f32_e32 v174, v75
	v_exp_f32_e32 v180, v76
	v_exp_f32_e32 v178, v77
	v_pk_add_f32 v[70:71], v[212:213], s[48:49] op_sel_hi:[0,1]
	v_pk_add_f32 v[72:73], v[212:213], s[54:55] op_sel_hi:[0,1]
	v_pk_add_f32 v[74:75], v[212:213], s[56:57] op_sel_hi:[0,1]
	v_pk_add_f32 v[76:77], v[212:213], s[58:59] op_sel_hi:[0,1]
	v_and_b32_e32 v213, 0x7fffffff, v81
	v_and_b32_e32 v212, 0x7fffffff, v80
	v_and_b32_e32 v215, 0x7fffffff, v79
	v_and_b32_e32 v214, 0x7fffffff, v78
	v_and_b32_e32 v69, 0x7fffffff, v69
	v_and_b32_e32 v68, 0x7fffffff, v68
	v_and_b32_e32 v67, 0x7fffffff, v67
	v_and_b32_e32 v66, 0x7fffffff, v66
	v_pk_fma_f32 v[80:81], v[110:111], v[66:67], v[146:147]
	v_pk_fma_f32 v[78:79], v[110:111], v[68:69], v[146:147]
	v_pk_fma_f32 v[68:69], v[110:111], v[214:215], v[146:147]
	v_pk_fma_f32 v[66:67], v[110:111], v[212:213], v[148:149]
	v_and_b32_e32 v217, 0x7fffffff, v77
	v_and_b32_e32 v216, 0x7fffffff, v76
	v_and_b32_e32 v219, 0x7fffffff, v75
	v_and_b32_e32 v218, 0x7fffffff, v74
	v_and_b32_e32 v73, 0x7fffffff, v73
	v_and_b32_e32 v72, 0x7fffffff, v72
	v_and_b32_e32 v71, 0x7fffffff, v71
	v_and_b32_e32 v70, 0x7fffffff, v70
	v_pk_fma_f32 v[76:77], v[110:111], v[70:71], v[146:147]
	v_pk_fma_f32 v[74:75], v[110:111], v[72:73], v[146:147]
	v_pk_fma_f32 v[72:73], v[110:111], v[218:219], v[146:147]
	v_pk_fma_f32 v[70:71], v[110:111], v[216:217], v[146:147]
	v_cvt_pk_bf16_f32 v103, v164, v162
	v_cvt_pk_bf16_f32 v104, v168, v166
	s_waitcnt lgkmcnt(3)
	v_mfma_f32_32x32x16_bf16 v[66:81], v[112:115], v[82:85], v[66:81]
	v_cvt_pk_bf16_f32 v105, v172, v170
	v_cvt_pk_bf16_f32 v98, v176, v174
	v_cvt_pk_bf16_f32 v99, v180, v178
	v_cvt_pk_bf16_f32 v100, v184, v182
	v_cvt_pk_bf16_f32 v101, v188, v186
	s_waitcnt lgkmcnt(2)
	v_mfma_f32_32x32x16_bf16 v[66:81], v[116:119], v[86:89], v[66:81]
	s_waitcnt lgkmcnt(1)
	v_mfma_f32_32x32x16_bf16 v[66:81], v[120:123], v[90:93], v[66:81]
	s_waitcnt lgkmcnt(0)
	s_barrier
	s_waitcnt lgkmcnt(0)
	v_mfma_f32_32x32x16_bf16 v[66:81], v[250:253], v[94:97], v[66:81]
	s_nop 11
	v_exp_f32_e32 v187, v80
	v_or_b32_e32 v80, s86, v193
	v_exp_f32_e32 v161, v81
	v_add_u32_e32 v81, v80, v195
	v_exp_f32_e32 v179, v76
	v_exp_f32_e32 v185, v77
	v_exp_f32_e32 v183, v78
	v_exp_f32_e32 v189, v79
	v_add_u32_e32 v127, v80, v196
	ds_read_b128 v[112:115], v81 offset:16384
	ds_read_b128 v[116:119], v127 offset:16384
	ds_read_b128 v[120:123], v81 offset:20480
	ds_read_b128 v[250:253], v127 offset:20480
	s_waitcnt lgkmcnt(3)
	v_mfma_f32_32x32x16_bf16 v[50:65], v[112:115], v[102:105], v[50:65]
	ds_read_b128 v[112:115], v81 offset:24576
	v_exp_f32_e32 v129, v66
	v_exp_f32_e32 v165, v67
	v_exp_f32_e32 v163, v68
	v_exp_f32_e32 v169, v69
	v_pk_add_f32 v[66:67], v[128:129], v[132:133]
	v_exp_f32_e32 v167, v70
	s_waitcnt lgkmcnt(3)
	v_mfma_f32_32x32x16_bf16 v[50:65], v[116:119], v[98:101], v[50:65]
	ds_read_b128 v[116:119], v127 offset:24576
	v_add_f32_e64 v66, v164, v66
	v_add_f32_e64 v67, v165, v67
	v_exp_f32_e32 v173, v71
	v_pk_add_f32 v[66:67], v[162:163], v[66:67]
	v_exp_f32_e32 v171, v72
	v_exp_f32_e32 v177, v73
	v_pk_add_f32 v[66:67], v[168:169], v[66:67]
	s_waitcnt lgkmcnt(3)
	v_mfma_f32_32x32x16_bf16 v[34:49], v[120:123], v[102:105], v[34:49]
	ds_read_b128 v[120:123], v81 offset:28672
	v_exp_f32_e32 v175, v74
	v_pk_add_f32 v[66:67], v[166:167], v[66:67]
	v_exp_f32_e32 v181, v75
	v_pk_add_f32 v[66:67], v[172:173], v[66:67]
	v_cvt_pk_bf16_f32 v70, v129, v165
	v_pk_add_f32 v[66:67], v[170:171], v[66:67]
	s_waitcnt lgkmcnt(3)
	v_mfma_f32_32x32x16_bf16 v[34:49], v[250:253], v[98:101], v[34:49]
	v_add_u32_e32 v81, v80, v197
	v_add_u32_e32 v80, v80, v198
	ds_read_b128 v[250:253], v127 offset:28672
	v_cvt_pk_bf16_f32 v71, v163, v169
	v_cvt_pk_bf16_f32 v72, v167, v173
	v_cvt_pk_bf16_f32 v73, v171, v177
	v_add_f32_e64 v66, v176, v66
	v_add_f32_e64 v67, v177, v67
	v_cvt_pk_bf16_f32 v68, v183, v189
	v_pk_add_f32 v[66:67], v[174:175], v[66:67]
	s_waitcnt lgkmcnt(3)
	v_mfma_f32_32x32x16_bf16 v[18:33], v[112:115], v[102:105], v[18:33]
	ds_read_b128 v[112:115], v81 offset:16384
	v_add_f32_e64 v66, v180, v66
	v_add_f32_e64 v67, v181, v67
	v_cvt_pk_bf16_f32 v69, v187, v161
	v_add_f32_e64 v66, v178, v66
	v_add_f32_e64 v67, v179, v67
	v_pk_add_f32 v[66:67], v[184:185], v[66:67]
	s_waitcnt lgkmcnt(3)
	v_mfma_f32_32x32x16_bf16 v[18:33], v[116:119], v[98:101], v[18:33]
	ds_read_b128 v[116:119], v80 offset:16384
	v_add_f32_e64 v66, v182, v66
	v_add_f32_e64 v67, v183, v67
	v_pk_add_f32 v[66:67], v[188:189], v[66:67]
	s_waitcnt lgkmcnt(3)
	v_mfma_f32_32x32x16_bf16 v[2:17], v[120:123], v[102:105], v[2:17]
	ds_read_b128 v[120:123], v81 offset:20480
	v_add_f32_e64 v66, v186, v66
	v_add_f32_e64 v67, v187, v67
	v_add_f32_e64 v74, v160, v66
	v_add_f32_e64 v75, v161, v67
	v_cvt_pk_bf16_f32 v66, v175, v181
	v_cvt_pk_bf16_f32 v67, v179, v185
	v_add_f32_e32 v160, v74, v75
	s_waitcnt lgkmcnt(3)
	v_mfma_f32_32x32x16_bf16 v[2:17], v[250:253], v[98:101], v[2:17]
	ds_read_b128 v[250:253], v80 offset:20480
	s_waitcnt lgkmcnt(3)
	v_mfma_f32_32x32x16_bf16 v[50:65], v[112:115], v[70:73], v[50:65]
	ds_read_b128 v[112:115], v81 offset:24576
	s_waitcnt lgkmcnt(3)
	v_mfma_f32_32x32x16_bf16 v[50:65], v[116:119], v[66:69], v[50:65]
	ds_read_b128 v[116:119], v80 offset:24576
	s_waitcnt lgkmcnt(3)
	v_mfma_f32_32x32x16_bf16 v[34:49], v[120:123], v[70:73], v[34:49]
	ds_read_b128 v[120:123], v81 offset:28672
	s_waitcnt lgkmcnt(3)
	v_mfma_f32_32x32x16_bf16 v[34:49], v[250:253], v[66:69], v[34:49]
	ds_read_b128 v[250:253], v80 offset:28672
	s_waitcnt lgkmcnt(3)
	v_mfma_f32_32x32x16_bf16 v[18:33], v[112:115], v[70:73], v[18:33]
	s_waitcnt lgkmcnt(2)
	v_mfma_f32_32x32x16_bf16 v[18:33], v[116:119], v[66:69], v[18:33]
	s_waitcnt lgkmcnt(1)
	v_mfma_f32_32x32x16_bf16 v[2:17], v[120:123], v[70:73], v[2:17]
	s_waitcnt lgkmcnt(0)
	v_mfma_f32_32x32x16_bf16 v[2:17], v[250:253], v[66:69], v[2:17]
	v_mov_b32_e32 v66, v126
	s_andn2_b64 exec, exec, s[84:85]
	s_cbranch_execz .LBB0_237

	.amdhsa_kernel _Z14fwd_megakernel6Params
		.amdhsa_group_segment_fixed_size 133120
		.amdhsa_private_segment_fixed_size 0
		.amdhsa_kernarg_size 648
		.amdhsa_user_sgpr_count 2
		.amdhsa_user_sgpr_dispatch_ptr 0
		.amdhsa_user_sgpr_queue_ptr 0
		.amdhsa_user_sgpr_kernarg_segment_ptr 1
		.amdhsa_user_sgpr_dispatch_id 0
		.amdhsa_user_sgpr_kernarg_preload_length 0
		.amdhsa_user_sgpr_kernarg_preload_offset 0
		.amdhsa_user_sgpr_private_segment_size 0
		.amdhsa_uses_dynamic_stack 0
		.amdhsa_enable_private_segment 0
		.amdhsa_system_sgpr_workgroup_id_x 1
		.amdhsa_system_sgpr_workgroup_id_y 0
		.amdhsa_system_sgpr_workgroup_id_z 0
		.amdhsa_system_sgpr_workgroup_info 0
		.amdhsa_system_vgpr_workitem_id 0
		.amdhsa_next_free_vgpr 256
		.amdhsa_next_free_sgpr 98
		.amdhsa_accum_offset 256
		.amdhsa_reserve_vcc 1
		.amdhsa_float_round_mode_32 0
		.amdhsa_float_round_mode_16_64 0
		.amdhsa_float_denorm_mode_32 3
		.amdhsa_float_denorm_mode_16_64 3
		.amdhsa_dx10_clamp 1
		.amdhsa_ieee_mode 1
		.amdhsa_fp16_overflow 0
		.amdhsa_tg_split 0
		.amdhsa_exception_fp_ieee_invalid_op 0
		.amdhsa_exception_fp_denorm_src 0
		.amdhsa_exception_fp_ieee_div_zero 0
		.amdhsa_exception_fp_ieee_overflow 0
		.amdhsa_exception_fp_ieee_underflow 0
		.amdhsa_exception_fp_ieee_inexact 0
		.amdhsa_exception_int_div_zero 0
	.end_amdhsa_kernel

.Lfunc_end0:
	.size	_Z14fwd_megakernel6Params, .Lfunc_end0-_Z14fwd_megakernel6Params
	.set _Z14fwd_megakernel6Params.num_vgpr, 256
	.set _Z14fwd_megakernel6Params.num_agpr, 0
	.set _Z14fwd_megakernel6Params.numbered_sgpr, 98
	.set _Z14fwd_megakernel6Params.num_named_barrier, 0
	.set _Z14fwd_megakernel6Params.private_seg_size, 0
	.set _Z14fwd_megakernel6Params.uses_vcc, 1
	.set _Z14fwd_megakernel6Params.uses_flat_scratch, 0
	.set _Z14fwd_megakernel6Params.has_dyn_sized_stack, 0
	.set _Z14fwd_megakernel6Params.has_recursion, 0
	.set _Z14fwd_megakernel6Params.has_indirect_call, 0

amdhsa.kernels:
  - .agpr_count:     0
    .args:
      - .offset:         0
        .size:           392
        .value_kind:     by_value
      - .offset:         392
        .size:           4
        .value_kind:     hidden_block_count_x
      - .offset:         396
        .size:           4
        .value_kind:     hidden_block_count_y
      - .offset:         400
        .size:           4
        .value_kind:     hidden_block_count_z
      - .offset:         404
        .size:           2
        .value_kind:     hidden_group_size_x
      - .offset:         406
        .size:           2
        .value_kind:     hidden_group_size_y
      - .offset:         408
        .size:           2
        .value_kind:     hidden_group_size_z
      - .offset:         410
        .size:           2
        .value_kind:     hidden_remainder_x
      - .offset:         412
        .size:           2
        .value_kind:     hidden_remainder_y
      - .offset:         414
        .size:           2
        .value_kind:     hidden_remainder_z
      - .offset:         432
        .size:           8
        .value_kind:     hidden_global_offset_x
      - .offset:         440
        .size:           8
        .value_kind:     hidden_global_offset_y
      - .offset:         448
        .size:           8
        .value_kind:     hidden_global_offset_z
      - .offset:         456
        .size:           2
        .value_kind:     hidden_grid_dims
    .group_segment_fixed_size: 133120
    .kernarg_segment_align: 8
    .kernarg_segment_size: 648
    .language:       OpenCL C
    .language_version:
      - 2
      - 0
    .max_flat_workgroup_size: 512
    .name:           _Z14fwd_megakernel6Params
    .private_segment_fixed_size: 0
    .sgpr_count:     104
    .sgpr_spill_count: 86
    .symbol:         _Z14fwd_megakernel6Params.kd
    .uniform_work_group_size: 1
    .uses_dynamic_stack: false
    .vgpr_count:     256
    .vgpr_spill_count: 0
    .wavefront_size: 64
